# chain v6 (y rows parked in an LDS ring and stored by a loader wave with full-line stores) + attention with blocked K/V layouts + sliding-window conv
# speedup vs baseline: 1.0049x; 1.0049x over previous
.LBB0_406:
	v_and_b32_e32 v1, 63, v0
	v_and_b32_e32 v2, 15, v1
	v_lshrrev_b32_e32 v3, 4, v1
	v_readfirstlane_b32 s6, v0
	s_lshr_b32 s7, s2, 4
	s_and_b32 s8, s2, 15
	s_nop 0
	s_lshr_b32 s6, s6, 6
	s_cmp_gt_u32 s6, 3
	s_cbranch_scc1 .Lser_loader
	v_lshrrev_b32_e32 v4, 1, v3
	v_and_b32_e32 v5, 1, v3
	v_lshlrev_b32_e32 v4, 8, v4
	v_lshl_add_u32 v4, v2, 4, v4
	v_lshl_add_u32 v4, v5, 3, v4
	s_lshl_b32 s12, s6, 4
	v_add_u32_e32 v5, s12, v2
	v_lshlrev_b32_e32 v6, 5, v5
	v_lshl_add_u32 v6, v3, 3, v6
	v_add_u32_e32 v6, 0x2400, v6
	v_lshlrev_b32_e32 v7, 9, v3
	v_lshl_add_u32 v7, v5, 1, v7
	v_add_u32_e32 v7, 0x2c00, v7
	v_lshrrev_b32_e32 v120, 2, v2
	v_lshlrev_b32_e32 v120, 6, v120
	v_lshl_add_u32 v120, v3, 4, v120
	v_and_b32_e32 v129, 3, v2
	v_lshl_add_u32 v120, v129, 2, v120
	v_add_u32_e32 v120, 0x3400, v120
	v_lshlrev_b32_e32 v119, 9, v3
	v_lshl_add_u32 v119, v5, 1, v119
	v_add_u32_e32 v119, 0x1c000, v119
	v_mov_b32_e32 v8, 0
	v_mov_b32_e32 v9, 0
	v_mov_b32_e32 v10, 0
	v_mov_b32_e32 v11, 0
	v_mov_b32_e32 v12, 0
	v_mov_b32_e32 v13, 0
	v_mov_b32_e32 v14, 0
	v_mov_b32_e32 v15, 0
	v_mov_b32_e32 v16, 0
	v_mov_b32_e32 v17, 0
	v_mov_b32_e32 v18, 0
	v_mov_b32_e32 v19, 0
	v_mov_b32_e32 v20, 0
	v_mov_b32_e32 v21, 0
	v_mov_b32_e32 v22, 0
	v_mov_b32_e32 v23, 0
	v_mov_b32_e32 v24, 0
	v_mov_b32_e32 v25, 0
	v_mov_b32_e32 v26, 0
	v_mov_b32_e32 v27, 0
	v_mov_b32_e32 v28, 0
	v_mov_b32_e32 v29, 0
	v_mov_b32_e32 v30, 0
	v_mov_b32_e32 v31, 0
	s_mov_b32 s10, 0
	s_mov_b32 s11, 0
	s_mov_b32 s19, 0x1800
	s_barrier
	v_add_u32_e32 v121, s10, v4
	v_add_u32_e32 v126, s10, v6
	v_add_u32_e32 v128, s10, v120
	v_add_u32_e32 v122, 0x800, v121
	ds_read_b64 v[48:49], v126
	ds_read2_b64 v[32:35], v121 offset1:64
	ds_read2_b64 v[36:39], v121 offset0:128 offset1:192
	ds_read2_b64 v[40:43], v122 offset1:64
	ds_read2_b64 v[44:47], v122 offset0:128 offset1:192
	ds_read_b32 v82, v128
	v_add_u32_e32 v127, s10, v7
	v_add_u32_e32 v123, 0x1000, v121
	v_add_u32_e32 v124, 0x1800, v121
	v_add_u32_e32 v125, 0x2000, v121
	ds_read_u16 v133, v127
	ds_read_u16 v134, v127 offset:128
	ds_read_u16 v135, v127 offset:256
	ds_read_u16 v136, v127 offset:384
	ds_read2_b64 v[62:65], v123 offset1:64
	ds_read2_b64 v[66:69], v123 offset0:128 offset1:192
	ds_read2_b64 v[70:73], v124 offset1:64
	ds_read2_b64 v[74:77], v124 offset0:128 offset1:192
	ds_read2_b64 v[78:81], v125 offset1:64
	s_add_u32 s10, s10, 0x3800
	s_cmp_eq_u32 s10, 0x1c000
	s_cselect_b32 s10, 0, s10
	s_waitcnt lgkmcnt(9)
	v_lshlrev_b32_e32 v50, 16, v48
	v_and_b32_e32 v51, 0xffff0000, v48
	v_lshlrev_b32_e32 v52, 16, v49
	v_and_b32_e32 v53, 0xffff0000, v49
.Lser_chain_loop:
	s_nop 1
	v_mfma_f32_16x16x32_bf16 v[50:53], v[32:35], v[24:27], v[50:53]
	v_add_u32_e32 v121, s10, v4
	v_add_u32_e32 v126, s10, v6
	v_add_u32_e32 v128, s10, v120
	v_mfma_f32_16x16x32_bf16 v[54:57], v[40:43], v[24:27], 0
	v_add_u32_e32 v122, 0x800, v121
	ds_read_b64 v[140:141], v126
	ds_read2_b64 v[142:145], v121 offset1:64
	v_mfma_f32_16x16x32_bf16 v[50:53], v[36:39], v[28:31], v[50:53]
	ds_read2_b64 v[146:149], v121 offset0:128 offset1:192
	ds_read2_b64 v[150:153], v122 offset1:64
	ds_read2_b64 v[154:157], v122 offset0:128 offset1:192
	v_mfma_f32_16x16x32_bf16 v[54:57], v[44:47], v[28:31], v[54:57]
	ds_read_b32 v158, v128
	v_mul_f32_dpp v98, v82, v8 row_newbcast:0 row_mask:0xf bank_mask:0xf
	v_mul_f32_dpp v99, v82, v9 row_newbcast:1 row_mask:0xf bank_mask:0xf
	v_mul_f32_dpp v100, v82, v10 row_newbcast:2 row_mask:0xf bank_mask:0xf
	v_mul_f32_dpp v101, v82, v11 row_newbcast:3 row_mask:0xf bank_mask:0xf
	v_mul_f32_dpp v102, v82, v12 row_newbcast:4 row_mask:0xf bank_mask:0xf
	v_mul_f32_dpp v103, v82, v13 row_newbcast:5 row_mask:0xf bank_mask:0xf
	v_mul_f32_dpp v104, v82, v14 row_newbcast:6 row_mask:0xf bank_mask:0xf
	v_mul_f32_dpp v105, v82, v15 row_newbcast:7 row_mask:0xf bank_mask:0xf
	v_mul_f32_dpp v106, v82, v16 row_newbcast:8 row_mask:0xf bank_mask:0xf
	v_mul_f32_dpp v107, v82, v17 row_newbcast:9 row_mask:0xf bank_mask:0xf
	v_mul_f32_dpp v108, v82, v18 row_newbcast:10 row_mask:0xf bank_mask:0xf
	v_mul_f32_dpp v109, v82, v19 row_newbcast:11 row_mask:0xf bank_mask:0xf
	v_mul_f32_dpp v110, v82, v20 row_newbcast:12 row_mask:0xf bank_mask:0xf
	v_mul_f32_dpp v111, v82, v21 row_newbcast:13 row_mask:0xf bank_mask:0xf
	v_mul_f32_dpp v112, v82, v22 row_newbcast:14 row_mask:0xf bank_mask:0xf
	v_mul_f32_dpp v113, v82, v23 row_newbcast:15 row_mask:0xf bank_mask:0xf
	s_barrier
	v_cvt_pk_bf16_f32 v58, v50, v51
	v_cvt_pk_bf16_f32 v59, v52, v53
	s_waitcnt lgkmcnt(6)
	v_lshl_or_b32 v60, v134, 16, v133
	v_lshl_or_b32 v61, v136, 16, v135
	s_nop 1
	v_mfma_f32_16x16x32_bf16 v[8:11], v[62:65], v[58:61], v[98:101]
	v_cvt_pk_bf16_f32 v114, v204, v204
	v_cvt_pk_bf16_f32 v115, v205, v205
	v_cvt_pk_bf16_f32 v131, v206, v206
	v_mfma_f32_16x16x32_bf16 v[12:15], v[66:69], v[58:61], v[102:105]
	v_cvt_pk_bf16_f32 v132, v207, v207
	v_add_u32_e32 v129, s19, v119
	ds_write_b16 v129, v114
	v_mfma_f32_16x16x32_bf16 v[16:19], v[70:73], v[58:61], v[106:109]
	ds_write_b16 v129, v115 offset:128
	ds_write_b16 v129, v131 offset:256
	ds_write_b16 v129, v132 offset:384
	v_mfma_f32_16x16x32_bf16 v[20:23], v[74:77], v[58:61], v[110:113]
	s_add_u32 s19, s19, 0x800
	s_and_b32 s19, s19, 0x1800
	v_add_u32_e32 v127, s10, v7
	v_mfma_f32_16x16x32_bf16 v[54:57], v[78:81], v[58:61], v[54:57]
	v_add_u32_e32 v123, 0x1000, v121
	v_add_u32_e32 v124, 0x1800, v121
	v_add_u32_e32 v125, 0x2000, v121
	ds_read_u16 v174, v127
	ds_read_u16 v175, v127 offset:128
	ds_read_u16 v176, v127 offset:256
	ds_read_u16 v177, v127 offset:384
	ds_read2_b64 v[184:187], v123 offset1:64
	ds_read2_b64 v[188:191], v123 offset0:128 offset1:192
	ds_read2_b64 v[192:195], v124 offset1:64
	ds_read2_b64 v[196:199], v124 offset0:128 offset1:192
	ds_read2_b64 v[200:203], v125 offset1:64
	s_add_u32 s10, s10, 0x3800
	s_cmp_eq_u32 s10, 0x1c000
	s_cselect_b32 s10, 0, s10
	v_cvt_pk_bf16_f32 v24, v8, v9
	v_cvt_pk_bf16_f32 v25, v10, v11
	v_cvt_pk_bf16_f32 v26, v12, v13
	v_cvt_pk_bf16_f32 v27, v14, v15
	v_cvt_pk_bf16_f32 v28, v16, v17
	v_cvt_pk_bf16_f32 v29, v18, v19
	v_cvt_pk_bf16_f32 v30, v20, v21
	v_cvt_pk_bf16_f32 v31, v22, v23
	s_waitcnt lgkmcnt(13)
	v_lshlrev_b32_e32 v50, 16, v140
	v_and_b32_e32 v51, 0xffff0000, v140
	v_lshlrev_b32_e32 v52, 16, v141
	v_and_b32_e32 v53, 0xffff0000, v141
	s_nop 1
	v_mfma_f32_16x16x32_bf16 v[50:53], v[142:145], v[24:27], v[50:53]
	v_add_u32_e32 v121, s10, v4
	v_add_u32_e32 v126, s10, v6
	v_add_u32_e32 v128, s10, v120
	v_mfma_f32_16x16x32_bf16 v[204:207], v[150:153], v[24:27], 0
	v_add_u32_e32 v122, 0x800, v121
	ds_read_b64 v[48:49], v126
	ds_read2_b64 v[32:35], v121 offset1:64
	v_mfma_f32_16x16x32_bf16 v[50:53], v[146:149], v[28:31], v[50:53]
	ds_read2_b64 v[36:39], v121 offset0:128 offset1:192
	ds_read2_b64 v[40:43], v122 offset1:64
	ds_read2_b64 v[44:47], v122 offset0:128 offset1:192
	v_mfma_f32_16x16x32_bf16 v[204:207], v[154:157], v[28:31], v[204:207]
	ds_read_b32 v82, v128
	v_mul_f32_dpp v98, v158, v8 row_newbcast:0 row_mask:0xf bank_mask:0xf
	v_mul_f32_dpp v99, v158, v9 row_newbcast:1 row_mask:0xf bank_mask:0xf
	v_mul_f32_dpp v100, v158, v10 row_newbcast:2 row_mask:0xf bank_mask:0xf
	v_mul_f32_dpp v101, v158, v11 row_newbcast:3 row_mask:0xf bank_mask:0xf
	v_mul_f32_dpp v102, v158, v12 row_newbcast:4 row_mask:0xf bank_mask:0xf
	v_mul_f32_dpp v103, v158, v13 row_newbcast:5 row_mask:0xf bank_mask:0xf
	v_mul_f32_dpp v104, v158, v14 row_newbcast:6 row_mask:0xf bank_mask:0xf
	v_mul_f32_dpp v105, v158, v15 row_newbcast:7 row_mask:0xf bank_mask:0xf
	v_mul_f32_dpp v106, v158, v16 row_newbcast:8 row_mask:0xf bank_mask:0xf
	v_mul_f32_dpp v107, v158, v17 row_newbcast:9 row_mask:0xf bank_mask:0xf
	v_mul_f32_dpp v108, v158, v18 row_newbcast:10 row_mask:0xf bank_mask:0xf
	v_mul_f32_dpp v109, v158, v19 row_newbcast:11 row_mask:0xf bank_mask:0xf
	v_mul_f32_dpp v110, v158, v20 row_newbcast:12 row_mask:0xf bank_mask:0xf
	v_mul_f32_dpp v111, v158, v21 row_newbcast:13 row_mask:0xf bank_mask:0xf
	v_mul_f32_dpp v112, v158, v22 row_newbcast:14 row_mask:0xf bank_mask:0xf
	v_mul_f32_dpp v113, v158, v23 row_newbcast:15 row_mask:0xf bank_mask:0xf
	s_barrier
	v_cvt_pk_bf16_f32 v180, v50, v51
	v_cvt_pk_bf16_f32 v181, v52, v53
	s_waitcnt lgkmcnt(6)
	v_lshl_or_b32 v182, v175, 16, v174
	v_lshl_or_b32 v183, v177, 16, v176
	s_nop 1
	v_mfma_f32_16x16x32_bf16 v[8:11], v[184:187], v[180:183], v[98:101]
	v_cvt_pk_bf16_f32 v114, v54, v54
	v_cvt_pk_bf16_f32 v115, v55, v55
	v_cvt_pk_bf16_f32 v131, v56, v56
	v_mfma_f32_16x16x32_bf16 v[12:15], v[188:191], v[180:183], v[102:105]
	v_cvt_pk_bf16_f32 v132, v57, v57
	v_add_u32_e32 v129, s19, v119
	ds_write_b16 v129, v114
	v_mfma_f32_16x16x32_bf16 v[16:19], v[192:195], v[180:183], v[106:109]
	ds_write_b16 v129, v115 offset:128
	ds_write_b16 v129, v131 offset:256
	ds_write_b16 v129, v132 offset:384
	v_mfma_f32_16x16x32_bf16 v[20:23], v[196:199], v[180:183], v[110:113]
	s_add_u32 s19, s19, 0x800
	s_and_b32 s19, s19, 0x1800
	v_add_u32_e32 v127, s10, v7
	v_mfma_f32_16x16x32_bf16 v[204:207], v[200:203], v[180:183], v[204:207]
	v_add_u32_e32 v123, 0x1000, v121
	v_add_u32_e32 v124, 0x1800, v121
	v_add_u32_e32 v125, 0x2000, v121
	ds_read_u16 v133, v127
	ds_read_u16 v134, v127 offset:128
	ds_read_u16 v135, v127 offset:256
	ds_read_u16 v136, v127 offset:384
	ds_read2_b64 v[62:65], v123 offset1:64
	ds_read2_b64 v[66:69], v123 offset0:128 offset1:192
	ds_read2_b64 v[70:73], v124 offset1:64
	ds_read2_b64 v[74:77], v124 offset0:128 offset1:192
	ds_read2_b64 v[78:81], v125 offset1:64
	s_add_u32 s10, s10, 0x3800
	s_cmp_eq_u32 s10, 0x1c000
	s_cselect_b32 s10, 0, s10
	v_cvt_pk_bf16_f32 v24, v8, v9
	v_cvt_pk_bf16_f32 v25, v10, v11
	v_cvt_pk_bf16_f32 v26, v12, v13
	v_cvt_pk_bf16_f32 v27, v14, v15
	v_cvt_pk_bf16_f32 v28, v16, v17
	v_cvt_pk_bf16_f32 v29, v18, v19
	v_cvt_pk_bf16_f32 v30, v20, v21
	v_cvt_pk_bf16_f32 v31, v22, v23
	s_waitcnt lgkmcnt(13)
	v_lshlrev_b32_e32 v50, 16, v48
	v_and_b32_e32 v51, 0xffff0000, v48
	v_lshlrev_b32_e32 v52, 16, v49
	v_and_b32_e32 v53, 0xffff0000, v49
	s_add_u32 s11, s11, 2
	s_cmp_lt_u32 s11, 0x100
	s_cbranch_scc1 .Lser_chain_loop
	s_nop 7
	v_cvt_pk_bf16_f32 v114, v204, v204
	v_cvt_pk_bf16_f32 v115, v205, v205
	v_cvt_pk_bf16_f32 v131, v206, v206
	v_cvt_pk_bf16_f32 v132, v207, v207
	v_add_u32_e32 v129, s19, v119
	ds_write_b16 v129, v114
	ds_write_b16 v129, v115 offset:128
	ds_write_b16 v129, v131 offset:256
	ds_write_b16 v129, v132 offset:384
	s_add_u32 s19, s19, 0x800
	s_and_b32 s19, s19, 0x1800
	s_waitcnt lgkmcnt(0)
	s_barrier
	s_branch .Lser_exit

.Lser_ld_loop:
	s_waitcnt vmcnt(16)
	s_barrier
	s_cmp_lt_u32 s29, 0xff
	s_cselect_b32 s72, s20, 0
	s_cselect_b32 s73, s21, 0
	s_cselect_b32 s74, s22, 0
	s_cselect_b32 s75, s23, 0
	s_add_u32 m0, s28, s24
	s_nop 0
	global_load_lds_dwordx4 v10, s[12:13]
	s_add_u32 s12, s12, s72
	s_addc_u32 s13, s13, 0
	s_add_u32 m0, s28, s25
	s_nop 0
	global_load_lds_dwordx4 v11, s[14:15]
	s_add_u32 s14, s14, s73
	s_addc_u32 s15, s15, 0
	s_add_u32 m0, s28, s26
	s_nop 0
	global_load_lds_dwordx4 v12, s[16:17]
	s_add_u32 s16, s16, s74
	s_addc_u32 s17, s17, 0
	s_add_u32 m0, s28, s27
	s_nop 0
	global_load_lds_dwordx4 v13, s[18:19]
	s_add_u32 s18, s18, s75
	s_addc_u32 s19, s19, 0
	s_add_u32 s28, s28, 0x3800
	s_cmp_eq_u32 s28, 0x1c000
	s_cselect_b32 s28, 0, s28
	s_add_u32 s29, s29, 1
	s_add_u32 s3, s3, 1
	s_cmp_lt_u32 s3, 0x100
	s_cbranch_scc1 .Lser_ld_loop
	s_barrier
	s_waitcnt vmcnt(0)
	s_branch .Lser_exit
.Lser_ld3_pro:
	s_lshl_b32 s76, s7, 23
	s_lshl_b32 s77, s8, 7
	s_add_u32 s76, s76, s77
	s_add_u32 s76, s76, 0x14a08000
	s_add_u32 s76, s70, s76
	s_addc_u32 s77, s71, 0
	v_lshlrev_b32_e32 v14, 11, v5
	v_lshl_add_u32 v14, v6, 4, v14
	v_add_u32_e32 v15, 0x4000, v14
	v_lshlrev_b32_e32 v16, 4, v1
	v_add_u32_e32 v16, 0x1c000, v16
	s_mov_b32 s80, 0x800
.Lser_ld3_pro2:
	s_cmp_lt_u32 s29, 0xff
	s_cselect_b32 s72, s20, 0
	s_cselect_b32 s73, s21, 0
	s_add_u32 m0, s28, s24
	s_nop 0
	global_load_lds_dwordx4 v10, s[12:13]
	s_add_u32 s12, s12, s72
	s_addc_u32 s13, s13, 0
	s_add_u32 m0, s28, s25
	s_nop 0
	global_load_lds_dwordx4 v11, s[14:15]
	s_add_u32 s14, s14, s73
	s_addc_u32 s15, s15, 0
	s_add_u32 s28, s28, 0x3800
	s_cmp_eq_u32 s28, 0x1c000
	s_cselect_b32 s28, 0, s28
	s_add_u32 s29, s29, 1
	global_store_dwordx4 v14, v[20:23], s[76:77]
	global_store_dwordx4 v15, v[24:27], s[76:77]
	s_cmp_lt_u32 s29, 7
	s_cbranch_scc1 .Lser_ld3_pro2
	s_waitcnt vmcnt(22)
	s_barrier
	s_mov_b32 s3, 0
.Lser_ld3_loop:
	s_waitcnt vmcnt(18)
	s_barrier
	s_cmp_lt_u32 s29, 0xff
	s_cselect_b32 s72, s20, 0
	s_cselect_b32 s73, s21, 0
	s_add_u32 m0, s28, s24
	s_nop 0
	global_load_lds_dwordx4 v10, s[12:13]
	s_add_u32 s12, s12, s72
	s_addc_u32 s13, s13, 0
	s_add_u32 m0, s28, s25
	s_nop 0
	global_load_lds_dwordx4 v11, s[14:15]
	s_add_u32 s14, s14, s73
	s_addc_u32 s15, s15, 0
	s_add_u32 s28, s28, 0x3800
	s_cmp_eq_u32 s28, 0x1c000
	s_cselect_b32 s28, 0, s28
	s_add_u32 s29, s29, 1
	v_add_u32_e32 v17, s80, v16
	ds_read_b128 v[20:23], v17
	ds_read_b128 v[24:27], v17 offset:1024
	s_waitcnt lgkmcnt(0)
	global_store_dwordx4 v14, v[20:23], s[76:77]
	global_store_dwordx4 v15, v[24:27], s[76:77]
	s_add_u32 s80, s80, 0x800
	s_and_b32 s80, s80, 0x1800
	s_cmp_ge_u32 s3, 3
	s_cselect_b32 s81, 0x8000, 0
	s_add_u32 s76, s76, s81
	s_addc_u32 s77, s77, 0
	s_add_u32 s3, s3, 1
	s_cmp_lt_u32 s3, 0x100
	s_cbranch_scc1 .Lser_ld3_loop
	s_barrier
	v_add_u32_e32 v17, s80, v16
	ds_read_b128 v[20:23], v17
	ds_read_b128 v[24:27], v17 offset:1024
	s_waitcnt lgkmcnt(0)
	global_store_dwordx4 v14, v[20:23], s[76:77]
	global_store_dwordx4 v15, v[24:27], s[76:77]
	s_add_u32 s80, s80, 0x800
	s_and_b32 s80, s80, 0x1800
	s_add_u32 s76, s76, 0x8000
	s_addc_u32 s77, s77, 0
	v_add_u32_e32 v17, s80, v16
	ds_read_b128 v[20:23], v17
	ds_read_b128 v[24:27], v17 offset:1024
	s_waitcnt lgkmcnt(0)
	global_store_dwordx4 v14, v[20:23], s[76:77]
	global_store_dwordx4 v15, v[24:27], s[76:77]
	s_add_u32 s80, s80, 0x800
	s_and_b32 s80, s80, 0x1800
	s_add_u32 s76, s76, 0x8000
	s_addc_u32 s77, s77, 0
	v_add_u32_e32 v17, s80, v16
	ds_read_b128 v[20:23], v17
	ds_read_b128 v[24:27], v17 offset:1024
	s_waitcnt lgkmcnt(0)
	global_store_dwordx4 v14, v[20:23], s[76:77]
	global_store_dwordx4 v15, v[24:27], s[76:77]
	s_add_u32 s80, s80, 0x800
	s_and_b32 s80, s80, 0x1800
	s_add_u32 s76, s76, 0x8000
	s_addc_u32 s77, s77, 0
	s_waitcnt vmcnt(0)
